# G2: every workgroup runs its split-K piece first (E3 slab write drains under the K-loops); on top of v26
# baseline (speedup 1.0000x reference)
; __device__ __forceinline__ bool next_unit(const Params& p, int gph, int i, Unit& u) {
;     ...
;   } else if (gph == 1) {
;     if (G == 256 && i >= 3) {
;       if (i > 3) return false;
;       const int su = c, part = su & 7; int pm, pn;
;       static_tile(36, 8, 256 + (su >> 3), pm, pn);
;       const int seg = part < 2 ? 0 : part < 6 ? 1 : 2;
;       const size_t ko = part * 512;
;       u.A = ws + WS_ACAT + ((size_t)pm * 256 * 4096 + ko) * 2; u.B = ws + WS_WCAT + ((size_t)pn * 256 * 4096 + ko) * 2;
;       u.nt = 8; u.kind = 17 + seg; u.pm = su; u.pn = pm * 8 + pn;
;       return true;
;     }
;     const int L = (i / 3) * G + c, seg = i % 3;
;     if (L >= (G == 256 ? 256 : 288)) return false;
;     static_tile(36, 8, L, u.pm, u.pn);
;     const size_t so = seg == 0 ? 0 : seg == 1 ? 1024 : 3072;
;     u.A = ws + WS_ACAT + ((size_t)u.pm * 256 * 4096 + so) * 2; u.B = ws + WS_WCAT + ((size_t)u.pn * 256 * 4096 + so) * 2;
;     u.nt = seg == 1 ? 32 : 16; u.kind = 9 + seg;
;     return true;
.LBB0_290:
	s_mov_b32 s100, 0
	s_mov_b32 s101, 0
	s_cmp_eq_u32 s74, 1
	s_cbranch_scc0 .Lpf_done
	s_cmpk_lg_u32 s28, 0x100
	s_cbranch_scc1 .Lpf_done
	s_mov_b32 s101, 1
	v_readlane_b32 s44, v254, 60
	v_readlane_b32 s45, v254, 61
	v_readlane_b32 s46, v254, 62
	v_readlane_b32 s47, v254, 63
	v_readlane_b32 s78, v255, 0
	v_readlane_b32 s76, v253, 51
	s_mov_b32 s77, 8
	s_mov_b32 s48, s92

; __device__ __forceinline__ bool next_unit(const Params& p, int gph, int i, Unit& u) {
;     ...
;   } else if (gph == 1) {
;     if (G == 256 && i >= 3) {
;       if (i > 3) return false;
;       const int su = c, part = su & 7; int pm, pn;
;       static_tile(36, 8, 256 + (su >> 3), pm, pn);
;       const int seg = part < 2 ? 0 : part < 6 ? 1 : 2;
;       const size_t ko = part * 512;
;       u.A = ws + WS_ACAT + ((size_t)pm * 256 * 4096 + ko) * 2; u.B = ws + WS_WCAT + ((size_t)pn * 256 * 4096 + ko) * 2;
;       u.nt = 8; u.kind = 17 + seg; u.pm = su; u.pn = pm * 8 + pn;
;       return true;
;     }
;     const int L = (i / 3) * G + c, seg = i % 3;
;     if (L >= (G == 256 ? 256 : 288)) return false;
;     static_tile(36, 8, L, u.pm, u.pn);
;     const size_t so = seg == 0 ? 0 : seg == 1 ? 1024 : 3072;
;     u.A = ws + WS_ACAT + ((size_t)u.pm * 256 * 4096 + so) * 2; u.B = ws + WS_WCAT + ((size_t)u.pn * 256 * 4096 + so) * 2;
;     u.nt = seg == 1 ? 32 : 16; u.kind = 9 + seg;
;     return true;
.LBB0_325:
	s_andn2_b64 vcc, exec, s[60:61]
	s_cbranch_vccnz .LBB0_345
	s_cmp_gt_i32 s74, 0
	s_mov_b64 s[60:61], -1
	s_cbranch_scc0 .LBB0_334
	v_readlane_b32 s54, v253, 32
	s_add_i32 s41, s101, 2
	s_cmp_lt_i32 s51, s41
	v_readlane_b32 s55, v253, 33
	s_cselect_b64 s[52:53], -1, 0
	s_xor_b64 s[54:55], s[54:55], -1
	s_or_b64 s[52:53], s[54:55], s[52:53]
	s_and_b64 vcc, exec, s[52:53]
	s_cbranch_vccz .LBB0_330
	s_sub_i32 s100, s86, s101
	s_mul_hi_i32 s49, s100, 0x55555556
	s_lshr_b32 s41, s49, 31
	s_add_i32 s49, s49, s41
	s_mul_i32 s41, s49, s28
	s_add_i32 s41, s41, s92
	v_readlane_b32 s52, v253, 34
	s_mov_b64 s[60:61], 0
	s_cmp_ge_i32 s41, s52
	s_mov_b64 s[58:59], 0
	s_mov_b64 s[54:55], s[36:37]
	s_mov_b64 s[56:57], s[38:39]
	s_mov_b32 s87, s35
	s_mov_b32 s52, s40
	s_mov_b32 s88, s29
	s_mov_b32 s53, s34
	s_cbranch_scc1 .LBB0_330
	s_ashr_i32 s52, s41, 31
	s_lshr_b32 s52, s52, 29
	s_add_i32 s52, s41, s52
	s_mul_i32 s49, s49, 3
	s_ashr_i32 s53, s52, 3
	s_and_b32 s52, s52, -8
	s_sub_i32 s49, s100, s49
	s_sub_i32 s41, s41, s52
	s_cmp_lt_i32 s41, 0
	s_cselect_b32 s52, 37, 36
	s_mul_i32 s41, s52, s41
	s_add_i32 s41, s41, s53
	s_ashr_i32 s52, s41, 31
	s_lshr_b32 s52, s52, 26
	s_add_i32 s52, s41, s52
	s_ashr_i32 s53, s52, 6
	s_lshl_b32 s54, s53, 3
	s_sub_i32 s53, 36, s54
	s_min_u32 s55, s53, 8
	s_andn2_b32 s52, s52, 63
	s_sub_i32 s41, s41, s52
	v_cvt_f32_ubyte0_e32 v66, s55
	v_cvt_f32_i32_e32 v64, s41
	v_rcp_iflag_f32_e32 v67, v66
	s_ashr_i32 s52, s41, 30
	s_or_b32 s56, s52, 1
	v_readlane_b32 s58, v254, 30
	v_mul_f32_e32 v67, v64, v67
	v_trunc_f32_e32 v67, v67
	v_fma_f32 v64, -v67, v66, v64
	v_cvt_i32_f32_e32 v67, v67
	v_cmp_ge_f32_e64 s[52:53], |v64|, v66
	s_and_b64 s[52:53], s[52:53], exec
	s_cselect_b32 s52, s56, 0
	v_readfirstlane_b32 s53, v67
	s_add_i32 s56, s53, s52
	s_mul_i32 s52, s56, s55
	s_sub_i32 s41, s41, s52
	s_sext_i32_i8 s41, s41
	s_add_i32 s52, s54, s41
	s_cmp_eq_u32 s49, 1
	s_movk_i32 s41, 0x1800
	s_cselect_b32 s41, 0x800, s41
	s_cselect_b32 s87, 32, 16
	s_cmp_lg_u32 s49, 0
	s_cselect_b32 s41, s41, 0
	s_ashr_i32 s53, s52, 31
	s_lshl_b64 s[54:55], s[52:53], 21
	v_readlane_b32 s59, v254, 31
	s_add_u32 s53, s58, s54
	s_addc_u32 s55, s59, s55
	s_add_u32 s54, s53, s41
	s_sext_i32_i8 s88, s56
	s_addc_u32 s55, s55, 0
	s_bfe_i64 s[56:57], s[56:57], 0x80000
	s_lshl_b64 s[56:57], s[56:57], 21
	v_readlane_b32 s53, v254, 24
	s_add_u32 s53, s53, s56
	v_readlane_b32 s56, v254, 25
	s_addc_u32 s57, s56, s57
	s_add_u32 s56, s53, s41
	s_addc_u32 s57, s57, 0
	s_add_i32 s53, s49, 9
	s_mov_b64 s[58:59], -1

; #define LAS __attribute__((address_space(3)))
; __global__ void __launch_bounds__(512, 2) fwd_megakernel(Params p) {
;   extern __shared__ __attribute__((aligned(16))) unsigned char shm[];
;   LAS unsigned char* lds = (LAS unsigned char*)shm;
;   cg::grid_group grid = cg::this_grid();
;   unsigned char* ws = p.ws;
;   if (p.ph_hi > 1000) grid.sync();
;   volatile LAS unsigned* xst = (volatile LAS unsigned*)(lds + LDS_CTL - 16);
;   if (threadIdx.x == 0) { xst[0] = 0u; xst[1] = 0u; }
;   __syncthreads();
;   const XcdBarrier xb = xcd_barrier_post((unsigned*)(ws + WS_BAR), xst);
	.amdhsa_kernel _Z14fwd_megakernel6Params
		.amdhsa_group_segment_fixed_size 0
		.amdhsa_private_segment_fixed_size 0
		.amdhsa_kernarg_size 480
		.amdhsa_user_sgpr_count 2
		.amdhsa_user_sgpr_dispatch_ptr 0
		.amdhsa_user_sgpr_queue_ptr 0
		.amdhsa_user_sgpr_kernarg_segment_ptr 1
		.amdhsa_user_sgpr_dispatch_id 0
		.amdhsa_user_sgpr_kernarg_preload_length 0
		.amdhsa_user_sgpr_kernarg_preload_offset 0
		.amdhsa_user_sgpr_private_segment_size 0
		.amdhsa_uses_dynamic_stack 0
		.amdhsa_enable_private_segment 0
		.amdhsa_system_sgpr_workgroup_id_x 1
		.amdhsa_system_sgpr_workgroup_id_y 0
		.amdhsa_system_sgpr_workgroup_id_z 0
		.amdhsa_system_sgpr_workgroup_info 0
		.amdhsa_system_vgpr_workitem_id 2
		.amdhsa_next_free_vgpr 256
		.amdhsa_next_free_sgpr 102
		.amdhsa_accum_offset 256
		.amdhsa_reserve_vcc 1
		.amdhsa_float_round_mode_32 0
		.amdhsa_float_round_mode_16_64 0
		.amdhsa_float_denorm_mode_32 3
		.amdhsa_float_denorm_mode_16_64 3
		.amdhsa_dx10_clamp 1
		.amdhsa_ieee_mode 1
		.amdhsa_fp16_overflow 0
		.amdhsa_tg_split 0
		.amdhsa_exception_fp_ieee_invalid_op 0
		.amdhsa_exception_fp_denorm_src 0
		.amdhsa_exception_fp_ieee_div_zero 0
		.amdhsa_exception_fp_ieee_overflow 0
		.amdhsa_exception_fp_ieee_underflow 0
		.amdhsa_exception_fp_ieee_inexact 0
		.amdhsa_exception_int_div_zero 0
	.end_amdhsa_kernel

; #define LAS __attribute__((address_space(3)))
; __global__ void __launch_bounds__(512, 2) fwd_megakernel(Params p) {
;   extern __shared__ __attribute__((aligned(16))) unsigned char shm[];
;   LAS unsigned char* lds = (LAS unsigned char*)shm;
;   cg::grid_group grid = cg::this_grid();
;   unsigned char* ws = p.ws;
;   if (p.ph_hi > 1000) grid.sync();
;   volatile LAS unsigned* xst = (volatile LAS unsigned*)(lds + LDS_CTL - 16);
;   if (threadIdx.x == 0) { xst[0] = 0u; xst[1] = 0u; }
;   __syncthreads();
;   const XcdBarrier xb = xcd_barrier_post((unsigned*)(ws + WS_BAR), xst);
amdhsa.kernels:
  - .agpr_count:     0
    .args:
      - .offset:         0
        .size:           224
        .value_kind:     by_value
      - .offset:         224
        .size:           4
        .value_kind:     hidden_block_count_x
      - .offset:         228
        .size:           4
        .value_kind:     hidden_block_count_y
      - .offset:         232
        .size:           4
        .value_kind:     hidden_block_count_z
      - .offset:         236
        .size:           2
        .value_kind:     hidden_group_size_x
      - .offset:         238
        .size:           2
        .value_kind:     hidden_group_size_y
      - .offset:         240
        .size:           2
        .value_kind:     hidden_group_size_z
      - .offset:         242
        .size:           2
        .value_kind:     hidden_remainder_x
      - .offset:         244
        .size:           2
        .value_kind:     hidden_remainder_y
      - .offset:         246
        .size:           2
        .value_kind:     hidden_remainder_z
      - .offset:         264
        .size:           8
        .value_kind:     hidden_global_offset_x
      - .offset:         272
        .size:           8
        .value_kind:     hidden_global_offset_y
      - .offset:         280
        .size:           8
        .value_kind:     hidden_global_offset_z
      - .offset:         288
        .size:           2
        .value_kind:     hidden_grid_dims
      - .offset:         312
        .size:           8
        .value_kind:     hidden_multigrid_sync_arg
      - .offset:         344
        .size:           4
        .value_kind:     hidden_dynamic_lds_size
    .group_segment_fixed_size: 0
    .kernarg_segment_align: 8
    .kernarg_segment_size: 480
    .language:       OpenCL C
    .language_version:
      - 2
      - 0
    .max_flat_workgroup_size: 512
    .name:           _Z14fwd_megakernel6Params
    .private_segment_fixed_size: 0
    .sgpr_count:     108
    .sgpr_spill_count: 348
    .symbol:         _Z14fwd_megakernel6Params.kd
    .uniform_work_group_size: 1
    .uses_dynamic_stack: false
    .vgpr_count:     256
    .vgpr_spill_count: 0
    .wavefront_size: 64
